# v18 + SSQ partial-sum stores merged: 4 single-dword 16-lane stores per half -> one 64-lane store (P8, P4 layer0)
# baseline (speedup 1.0000x reference)
.LBB0_1011:
	v_mov_b32_e32 v184, v212
	s_lshl_b32 s11, s42, 8
	v_ashrrev_i32_e32 v136, 2, v184
	s_or_b32 s11, s11, s36
	v_and_b32_e32 v136, -4, v136
	v_add_u32_e32 v136, s11, v136
	v_and_or_b32 v138, v184, 15, s35
	s_lshl_b32 s11, s43, 8
	v_ashrrev_i32_e32 v137, 31, v136
	v_add_u32_e32 v140, s11, v138
	v_lshlrev_b64 v[136:137], 1, v[136:137]
	v_ashrrev_i32_e32 v141, 31, v140
	v_or_b32_e32 v150, 16, v140
	v_lshl_add_u64 v[138:139], s[4:5], 0, v[136:137]
	v_lshlrev_b64 v[168:169], 11, v[140:141]
	v_ashrrev_i32_e32 v151, 31, v150
	v_or_b32_e32 v154, 32, v140
	v_lshl_add_u64 v[142:143], v[138:139], 0, v[168:169]
	v_lshlrev_b64 v[170:171], 11, v[150:151]
	v_ashrrev_i32_e32 v155, 31, v154
	global_load_dwordx2 v[144:145], v[142:143], off
	global_load_dwordx2 v[146:147], v[142:143], off offset:32
	global_load_dwordx2 v[148:149], v[142:143], off offset:256
	global_load_dwordx2 v[152:153], v[142:143], off offset:288
	v_lshl_add_u64 v[142:143], v[138:139], 0, v[170:171]
	v_lshlrev_b64 v[154:155], 11, v[154:155]
	v_or_b32_e32 v174, 48, v140
	global_load_dwordx2 v[150:151], v[142:143], off
	global_load_dwordx2 v[156:157], v[142:143], off offset:32
	global_load_dwordx2 v[158:159], v[142:143], off offset:256
	global_load_dwordx2 v[160:161], v[142:143], off offset:288
	v_lshl_add_u64 v[142:143], v[138:139], 0, v[154:155]
	v_ashrrev_i32_e32 v175, 31, v174
	global_load_dwordx2 v[162:163], v[142:143], off
	global_load_dwordx2 v[164:165], v[142:143], off offset:32
	global_load_dwordx2 v[172:173], v[142:143], off offset:256
	global_load_dwordx2 v[176:177], v[142:143], off offset:288
	v_lshlrev_b64 v[142:143], 11, v[174:175]
	v_lshl_add_u64 v[174:175], v[138:139], 0, v[142:143]
	global_load_dwordx2 v[178:179], v[174:175], off
	global_load_dwordx2 v[180:181], v[174:175], off offset:32
	global_load_dwordx2 v[182:183], v[174:175], off offset:256
	s_nop 0
	global_load_dwordx2 v[174:175], v[174:175], off offset:288
	v_cmp_gt_u32_e32 vcc, 16, v184
	v_add_u32_e32 v141, s35, v184
	v_lshl_add_u64 v[168:169], s[4:5], 0, v[168:169]
	v_lshl_add_u64 v[168:169], v[168:169], 0, v[136:137]
	s_waitcnt vmcnt(0)
	v_lshlrev_b32_e32 v184, 16, v144
	v_and_b32_e32 v185, 0xffff0000, v144
	v_lshlrev_b32_e32 v186, 16, v145
	v_and_b32_e32 v187, 0xffff0000, v145
	v_pk_add_f32 v[126:127], v[126:127], v[184:185]
	v_pk_add_f32 v[128:129], v[128:129], v[186:187]
	v_lshlrev_b32_e32 v188, 16, v146
	v_and_b32_e32 v189, 0xffff0000, v146
	v_lshlrev_b32_e32 v190, 16, v147
	v_and_b32_e32 v191, 0xffff0000, v147
	v_pk_add_f32 v[122:123], v[122:123], v[188:189]
	v_pk_add_f32 v[124:125], v[124:125], v[190:191]
	v_lshlrev_b32_e32 v192, 16, v148
	v_and_b32_e32 v193, 0xffff0000, v148
	v_lshlrev_b32_e32 v194, 16, v149
	v_lshlrev_b32_e32 v144, 16, v174
	v_and_b32_e32 v145, 0xffff0000, v174
	v_cvt_pk_bf16_f32 v174, v126, v127
	v_mul_f32_e32 v127, v127, v127
	v_fmac_f32_e32 v127, v126, v126
	v_mul_f32_e32 v126, v129, v129
	v_fmac_f32_e32 v126, v128, v128
	v_lshlrev_b32_e32 v146, 16, v175
	v_and_b32_e32 v147, 0xffff0000, v175
	v_cvt_pk_bf16_f32 v175, v128, v129
	v_add_f32_e32 v128, v127, v126
	v_cvt_pk_bf16_f32 v126, v122, v123
	v_mul_f32_e32 v123, v123, v123
	v_fmac_f32_e32 v123, v122, v122
	v_mul_f32_e32 v122, v125, v125
	v_fmac_f32_e32 v122, v124, v124
	v_and_b32_e32 v195, 0xffff0000, v149
	v_add_f32_e32 v122, v123, v122
	v_pk_add_f32 v[118:119], v[118:119], v[192:193]
	v_cvt_pk_bf16_f32 v127, v124, v125
	v_add_f32_e32 v124, v128, v122
	v_pk_add_f32 v[120:121], v[120:121], v[194:195]
	v_cvt_pk_bf16_f32 v122, v118, v119
	v_mul_f32_e32 v119, v119, v119
	v_fmac_f32_e32 v119, v118, v118
	v_mul_f32_e32 v118, v121, v121
	v_lshlrev_b32_e32 v196, 16, v152
	v_and_b32_e32 v197, 0xffff0000, v152
	v_fmac_f32_e32 v118, v120, v120
	v_lshlrev_b32_e32 v198, 16, v153
	v_and_b32_e32 v199, 0xffff0000, v153
	v_add_f32_e32 v118, v119, v118
	v_pk_add_f32 v[110:111], v[110:111], v[196:197]
	v_cvt_pk_bf16_f32 v123, v120, v121
	v_add_f32_e32 v120, v124, v118
	v_pk_add_f32 v[112:113], v[112:113], v[198:199]
	v_cvt_pk_bf16_f32 v118, v110, v111
	v_mul_f32_e32 v111, v111, v111
	v_fmac_f32_e32 v111, v110, v110
	v_mul_f32_e32 v110, v113, v113
	v_fmac_f32_e32 v110, v112, v112
	v_lshlrev_b32_e32 v202, 16, v151
	v_and_b32_e32 v203, 0xffff0000, v151
	v_cvt_pk_bf16_f32 v119, v112, v113
	v_add_f32_e32 v110, v111, v110
	v_lshlrev_b32_e32 v200, 16, v150
	v_and_b32_e32 v201, 0xffff0000, v150
	v_lshlrev_b32_e32 v204, 16, v156
	v_and_b32_e32 v205, 0xffff0000, v156
	global_store_dwordx2 v[168:169], v[118:119], off offset:288
	v_add_u32_e32 v128, 0x80, v140
	v_ashrrev_i32_e32 v129, 31, v128
	v_lshlrev_b64 v[128:129], 11, v[128:129]
	v_lshl_add_u64 v[128:129], v[138:139], 0, v[128:129]
	v_mov_b32_e32 v124, 0x8000
	v_mov_b32_e32 v125, 0
	global_load_dwordx2 v[250:251], v[128:129], off
	global_load_dwordx2 v[248:249], v[128:129], off offset:32
	global_load_dwordx2 v[246:247], v[128:129], off offset:256
	global_load_dwordx2 v[244:245], v[128:129], off offset:288
	v_lshl_add_u64 v[128:129], v[128:129], 0, v[124:125]
	global_load_dwordx2 v[242:243], v[128:129], off
	global_load_dwordx2 v[240:241], v[128:129], off offset:32
	global_load_dwordx2 v[238:239], v[128:129], off offset:256
	global_load_dwordx2 v[236:237], v[128:129], off offset:288
	v_lshl_add_u64 v[128:129], v[128:129], 0, v[124:125]
	global_load_dwordx2 v[198:199], v[128:129], off
	global_load_dwordx2 v[196:197], v[128:129], off offset:32
	global_load_dwordx2 v[194:195], v[128:129], off offset:256
	global_load_dwordx2 v[192:193], v[128:129], off offset:288
	v_lshl_add_u64 v[128:129], v[128:129], 0, v[124:125]
	global_load_dwordx2 v[190:191], v[128:129], off
	global_load_dwordx2 v[188:189], v[128:129], off offset:32
	global_load_dwordx2 v[186:187], v[128:129], off offset:256
	global_load_dwordx2 v[184:185], v[128:129], off offset:288
	v_add_f32_e32 v118, v120, v110
	v_pk_add_f32 v[110:111], v[116:117], v[202:203]
	v_lshlrev_b32_e32 v206, 16, v157
	v_and_b32_e32 v207, 0xffff0000, v157
	v_pk_add_f32 v[112:113], v[114:115], v[200:201]
	v_cvt_pk_bf16_f32 v115, v110, v111
	v_mul_f32_e32 v111, v111, v111
	v_pk_add_f32 v[106:107], v[106:107], v[204:205]
	v_fmac_f32_e32 v111, v110, v110
	v_pk_add_f32 v[108:109], v[108:109], v[206:207]
	v_cvt_pk_bf16_f32 v110, v106, v107
	v_mul_f32_e32 v107, v107, v107
	v_cvt_pk_bf16_f32 v114, v112, v113
	v_mul_f32_e32 v113, v113, v113
	v_fmac_f32_e32 v107, v106, v106
	v_mul_f32_e32 v106, v109, v109
	v_lshlrev_b32_e32 v210, 16, v158
	v_and_b32_e32 v211, 0xffff0000, v158
	v_fmac_f32_e32 v113, v112, v112
	v_fmac_f32_e32 v106, v108, v108
	v_lshlrev_b32_e32 v214, 16, v159
	v_and_b32_e32 v215, 0xffff0000, v159
	v_add_f32_e32 v112, v113, v111
	v_add_f32_e32 v106, v107, v106
	v_pk_add_f32 v[102:103], v[102:103], v[210:211]
	v_cvt_pk_bf16_f32 v111, v108, v109
	v_add_f32_e32 v108, v112, v106
	v_pk_add_f32 v[104:105], v[104:105], v[214:215]
	v_cvt_pk_bf16_f32 v106, v102, v103
	v_mul_f32_e32 v103, v103, v103
	v_fmac_f32_e32 v103, v102, v102
	v_mul_f32_e32 v102, v105, v105
	v_lshlrev_b32_e32 v216, 16, v160
	v_and_b32_e32 v217, 0xffff0000, v160
	v_fmac_f32_e32 v102, v104, v104
	v_lshlrev_b32_e32 v224, 16, v161
	v_and_b32_e32 v225, 0xffff0000, v161
	v_add_f32_e32 v102, v103, v102
	v_pk_add_f32 v[94:95], v[94:95], v[216:217]
	v_cvt_pk_bf16_f32 v107, v104, v105
	v_add_f32_e32 v104, v108, v102
	v_pk_add_f32 v[96:97], v[96:97], v[224:225]
	v_cvt_pk_bf16_f32 v102, v94, v95
	v_mul_f32_e32 v95, v95, v95
	v_fmac_f32_e32 v95, v94, v94
	v_mul_f32_e32 v94, v97, v97
	v_lshl_add_u64 v[116:117], s[4:5], 0, v[170:171]
	v_fmac_f32_e32 v94, v96, v96
	v_lshlrev_b32_e32 v228, 16, v163
	v_and_b32_e32 v229, 0xffff0000, v163
	v_lshl_add_u64 v[116:117], v[116:117], 0, v[136:137]
	v_cvt_pk_bf16_f32 v103, v96, v97
	v_add_f32_e32 v94, v95, v94
	v_lshlrev_b32_e32 v226, 16, v162
	v_and_b32_e32 v227, 0xffff0000, v162
	v_lshlrev_b32_e32 v230, 16, v164
	v_and_b32_e32 v231, 0xffff0000, v164
	global_store_dwordx2 v[116:117], v[102:103], off offset:288
	v_add_f32_e32 v102, v104, v94
	v_pk_add_f32 v[94:95], v[100:101], v[228:229]
	v_lshlrev_b32_e32 v232, 16, v165
	v_and_b32_e32 v233, 0xffff0000, v165
	v_pk_add_f32 v[96:97], v[98:99], v[226:227]
	v_cvt_pk_bf16_f32 v99, v94, v95
	v_mul_f32_e32 v95, v95, v95
	v_pk_add_f32 v[90:91], v[90:91], v[230:231]
	v_fmac_f32_e32 v95, v94, v94
	v_pk_add_f32 v[92:93], v[92:93], v[232:233]
	v_cvt_pk_bf16_f32 v94, v90, v91
	v_mul_f32_e32 v91, v91, v91
	v_cvt_pk_bf16_f32 v98, v96, v97
	v_mul_f32_e32 v97, v97, v97
	v_fmac_f32_e32 v91, v90, v90
	v_mul_f32_e32 v90, v93, v93
	v_lshlrev_b32_e32 v234, 16, v172
	v_and_b32_e32 v235, 0xffff0000, v172
	v_fmac_f32_e32 v97, v96, v96
	v_fmac_f32_e32 v90, v92, v92
	v_lshlrev_b32_e32 v172, 16, v173
	v_and_b32_e32 v173, 0xffff0000, v173
	v_add_f32_e32 v96, v97, v95
	v_add_f32_e32 v90, v91, v90
	v_pk_add_f32 v[86:87], v[86:87], v[234:235]
	v_cvt_pk_bf16_f32 v95, v92, v93
	v_add_f32_e32 v92, v96, v90
	v_pk_add_f32 v[88:89], v[88:89], v[172:173]
	v_cvt_pk_bf16_f32 v90, v86, v87
	v_mul_f32_e32 v87, v87, v87
	v_fmac_f32_e32 v87, v86, v86
	v_mul_f32_e32 v86, v89, v89
	v_lshlrev_b32_e32 v162, 16, v176
	v_and_b32_e32 v163, 0xffff0000, v176
	v_fmac_f32_e32 v86, v88, v88
	v_lshlrev_b32_e32 v164, 16, v177
	v_and_b32_e32 v165, 0xffff0000, v177
	v_add_f32_e32 v86, v87, v86
	v_pk_add_f32 v[78:79], v[78:79], v[162:163]
	v_cvt_pk_bf16_f32 v91, v88, v89
	v_add_f32_e32 v88, v92, v86
	v_pk_add_f32 v[80:81], v[80:81], v[164:165]
	v_cvt_pk_bf16_f32 v86, v78, v79
	v_mul_f32_e32 v79, v79, v79
	v_fmac_f32_e32 v79, v78, v78
	v_mul_f32_e32 v78, v81, v81
	v_lshl_add_u64 v[100:101], s[4:5], 0, v[154:155]
	v_fmac_f32_e32 v78, v80, v80
	v_lshlrev_b32_e32 v160, 16, v179
	v_and_b32_e32 v161, 0xffff0000, v179
	v_lshl_add_u64 v[100:101], v[100:101], 0, v[136:137]
	v_cvt_pk_bf16_f32 v87, v80, v81
	v_add_f32_e32 v78, v79, v78
	v_lshlrev_b32_e32 v158, 16, v178
	v_and_b32_e32 v159, 0xffff0000, v178
	v_lshlrev_b32_e32 v152, 16, v180
	v_and_b32_e32 v153, 0xffff0000, v180
	global_store_dwordx2 v[100:101], v[86:87], off offset:288
	v_add_f32_e32 v86, v88, v78
	v_pk_add_f32 v[78:79], v[84:85], v[160:161]
	v_lshlrev_b32_e32 v156, 16, v181
	v_and_b32_e32 v157, 0xffff0000, v181
	v_pk_add_f32 v[80:81], v[82:83], v[158:159]
	v_cvt_pk_bf16_f32 v83, v78, v79
	v_mul_f32_e32 v79, v79, v79
	v_pk_add_f32 v[74:75], v[74:75], v[152:153]
	v_fmac_f32_e32 v79, v78, v78
	v_pk_add_f32 v[76:77], v[76:77], v[156:157]
	v_cvt_pk_bf16_f32 v78, v74, v75
	v_mul_f32_e32 v75, v75, v75
	v_cvt_pk_bf16_f32 v82, v80, v81
	v_mul_f32_e32 v81, v81, v81
	v_fmac_f32_e32 v75, v74, v74
	v_mul_f32_e32 v74, v77, v77
	v_lshlrev_b32_e32 v148, 16, v182
	v_and_b32_e32 v149, 0xffff0000, v182
	v_fmac_f32_e32 v81, v80, v80
	v_fmac_f32_e32 v74, v76, v76
	v_lshlrev_b32_e32 v150, 16, v183
	v_and_b32_e32 v151, 0xffff0000, v183
	v_add_f32_e32 v80, v81, v79
	v_add_f32_e32 v74, v75, v74
	v_pk_add_f32 v[70:71], v[70:71], v[148:149]
	v_cvt_pk_bf16_f32 v79, v76, v77
	v_add_f32_e32 v76, v80, v74
	v_pk_add_f32 v[72:73], v[72:73], v[150:151]
	v_cvt_pk_bf16_f32 v74, v70, v71
	v_mul_f32_e32 v71, v71, v71
	v_fmac_f32_e32 v71, v70, v70
	v_mul_f32_e32 v70, v73, v73
	v_fmac_f32_e32 v70, v72, v72
	v_add_f32_e32 v70, v71, v70
	v_pk_add_f32 v[66:67], v[66:67], v[144:145]
	v_cvt_pk_bf16_f32 v75, v72, v73
	v_add_f32_e32 v72, v76, v70
	v_pk_add_f32 v[68:69], v[68:69], v[146:147]
	v_cvt_pk_bf16_f32 v70, v66, v67
	v_mul_f32_e32 v67, v67, v67
	v_fmac_f32_e32 v67, v66, v66
	v_mul_f32_e32 v66, v69, v69
	v_fmac_f32_e32 v66, v68, v68
	v_lshl_add_u64 v[84:85], s[4:5], 0, v[142:143]
	v_add_f32_e32 v66, v67, v66
	v_lshl_add_u64 v[84:85], v[84:85], 0, v[136:137]
	v_cvt_pk_bf16_f32 v71, v68, v69
	v_add_f32_e32 v66, v72, v66
	global_store_dwordx2 v[84:85], v[70:71], off offset:288
	v_mov_b32_e32 v67, v118
	v_mov_b32_e32 v68, v102
	v_mov_b32_e32 v69, v86
	v_mov_b32_e32 v70, v66
	v_permlane16_swap_b32_e32 v118, v67
	v_permlane16_swap_b32_e32 v102, v68
	v_permlane16_swap_b32_e32 v86, v69
	v_permlane16_swap_b32_e32 v66, v70
	v_add_f32_e32 v67, v118, v67
	v_add_f32_e32 v68, v102, v68
	v_add_f32_e32 v69, v86, v69
	v_add_f32_e32 v71, v66, v70
	global_store_dwordx2 v[84:85], v[74:75], off offset:256
	v_mov_b32_e32 v70, v67
	v_mov_b32_e32 v72, v68
	v_mov_b32_e32 v73, v69
	v_mov_b32_e32 v74, v71
	v_permlane32_swap_b32_e32 v67, v70
	v_permlane32_swap_b32_e32 v68, v72
	v_permlane32_swap_b32_e32 v69, v73
	v_permlane32_swap_b32_e32 v71, v74
	v_add_u32_e32 v66, s11, v141
	global_store_dwordx2 v[168:169], v[174:175], off
	global_store_dwordx2 v[168:169], v[126:127], off offset:32
	global_store_dwordx2 v[168:169], v[122:123], off offset:256
	global_store_dwordx2 v[116:117], v[114:115], off
	global_store_dwordx2 v[116:117], v[110:111], off offset:32
	global_store_dwordx2 v[116:117], v[106:107], off offset:256
	global_store_dwordx2 v[100:101], v[98:99], off
	global_store_dwordx2 v[100:101], v[94:95], off offset:32
	global_store_dwordx2 v[100:101], v[90:91], off offset:256
	global_store_dwordx2 v[84:85], v[82:83], off
	global_store_dwordx2 v[84:85], v[78:79], off offset:32
	s_lshl_b32 s20, s42, 2
	s_ashr_i32 s21, s20, 31
	s_lshl_b64 s[20:21], s[20:21], 2
	s_add_u32 s20, s39, s20
	s_addc_u32 s21, s40, s21
	v_add_f32_e32 v70, v67, v70
	v_add_f32_e32 v73, v69, v73
	v_add_f32_e32 v72, v68, v72
	v_add_f32_e32 v71, v71, v74
	v_lshrrev_b32_e32 v74, 4, v212
	v_ashrrev_i32_e32 v67, 31, v66
	v_cmp_eq_u32_e64 s[18:19], 1, v74
	v_lshlrev_b64 v[68:69], 6, v[66:67]
	v_lshl_add_u64 v[68:69], s[20:21], 0, v[68:69]
	v_cndmask_b32_e64 v70, v70, v72, s[18:19]
	v_cmp_eq_u32_e64 s[18:19], 2, v74
	s_nop 1
	v_cndmask_b32_e64 v70, v70, v73, s[18:19]
	v_cmp_eq_u32_e64 s[18:19], 3, v74
	s_nop 1
	v_cndmask_b32_e64 v70, v70, v71, s[18:19]
	global_store_dword v[68:69], v70, off
.LBB0_1013:
	v_add_u32_e32 v68, 0x80, v140
	v_ashrrev_i32_e32 v69, 31, v68
	v_add_u32_e32 v76, 0x90, v140
	v_lshlrev_b64 v[92:93], 11, v[68:69]
	v_ashrrev_i32_e32 v77, 31, v76
	v_add_u32_e32 v80, 0xa0, v140
	v_lshl_add_u64 v[68:69], v[138:139], 0, v[92:93]
	v_lshlrev_b64 v[94:95], 11, v[76:77]
	v_ashrrev_i32_e32 v81, 31, v80
	v_lshl_add_u64 v[68:69], v[138:139], 0, v[94:95]
	v_lshlrev_b64 v[80:81], 11, v[80:81]
	v_add_u32_e32 v98, 0xb0, v140
	v_lshl_add_u64 v[68:69], v[138:139], 0, v[80:81]
	v_ashrrev_i32_e32 v99, 31, v98
	v_lshlrev_b64 v[68:69], 11, v[98:99]
	v_lshl_add_u64 v[98:99], v[138:139], 0, v[68:69]
	v_lshl_add_u64 v[92:93], s[4:5], 0, v[92:93]
	v_lshl_add_u64 v[92:93], v[92:93], 0, v[136:137]
	s_waitcnt vmcnt(15)
	v_lshlrev_b32_e32 v108, 16, v250
	v_and_b32_e32 v109, 0xffff0000, v250
	v_lshlrev_b32_e32 v110, 16, v251
	v_and_b32_e32 v111, 0xffff0000, v251
	v_pk_add_f32 v[62:63], v[62:63], v[108:109]
	v_pk_add_f32 v[64:65], v[64:65], v[110:111]
	v_lshlrev_b32_e32 v112, 16, v248
	v_and_b32_e32 v113, 0xffff0000, v248
	v_lshlrev_b32_e32 v114, 16, v249
	v_and_b32_e32 v115, 0xffff0000, v249
	v_pk_add_f32 v[58:59], v[58:59], v[112:113]
	v_pk_add_f32 v[60:61], v[60:61], v[114:115]
	v_lshlrev_b32_e32 v116, 16, v246
	v_and_b32_e32 v117, 0xffff0000, v246
	v_lshlrev_b32_e32 v118, 16, v247
	v_lshlrev_b32_e32 v70, 16, v184
	v_and_b32_e32 v71, 0xffff0000, v184
	v_cvt_pk_bf16_f32 v98, v62, v63
	v_mul_f32_e32 v63, v63, v63
	v_fmac_f32_e32 v63, v62, v62
	v_mul_f32_e32 v62, v65, v65
	v_fmac_f32_e32 v62, v64, v64
	v_lshlrev_b32_e32 v72, 16, v185
	v_and_b32_e32 v73, 0xffff0000, v185
	v_cvt_pk_bf16_f32 v99, v64, v65
	v_add_f32_e32 v64, v63, v62
	v_cvt_pk_bf16_f32 v62, v58, v59
	v_mul_f32_e32 v59, v59, v59
	v_fmac_f32_e32 v59, v58, v58
	v_mul_f32_e32 v58, v61, v61
	v_fmac_f32_e32 v58, v60, v60
	v_and_b32_e32 v119, 0xffff0000, v247
	v_add_f32_e32 v58, v59, v58
	v_pk_add_f32 v[54:55], v[54:55], v[116:117]
	v_cvt_pk_bf16_f32 v63, v60, v61
	v_add_f32_e32 v60, v64, v58
	v_pk_add_f32 v[56:57], v[56:57], v[118:119]
	v_cvt_pk_bf16_f32 v58, v54, v55
	v_mul_f32_e32 v55, v55, v55
	v_fmac_f32_e32 v55, v54, v54
	v_mul_f32_e32 v54, v57, v57
	v_lshlrev_b32_e32 v120, 16, v244
	v_and_b32_e32 v121, 0xffff0000, v244
	v_fmac_f32_e32 v54, v56, v56
	v_lshlrev_b32_e32 v122, 16, v245
	v_and_b32_e32 v123, 0xffff0000, v245
	v_add_f32_e32 v54, v55, v54
	v_pk_add_f32 v[46:47], v[46:47], v[120:121]
	v_cvt_pk_bf16_f32 v59, v56, v57
	v_add_f32_e32 v56, v60, v54
	v_pk_add_f32 v[48:49], v[48:49], v[122:123]
	v_cvt_pk_bf16_f32 v54, v46, v47
	v_mul_f32_e32 v47, v47, v47
	v_fmac_f32_e32 v47, v46, v46
	v_mul_f32_e32 v46, v49, v49
	v_fmac_f32_e32 v46, v48, v48
	v_lshlrev_b32_e32 v126, 16, v243
	v_and_b32_e32 v127, 0xffff0000, v243
	v_cvt_pk_bf16_f32 v55, v48, v49
	v_add_f32_e32 v46, v47, v46
	v_lshlrev_b32_e32 v124, 16, v242
	v_and_b32_e32 v125, 0xffff0000, v242
	v_lshlrev_b32_e32 v128, 16, v240
	v_and_b32_e32 v129, 0xffff0000, v240
	global_store_dwordx2 v[92:93], v[54:55], off offset:288
	v_add_f32_e32 v54, v56, v46
	v_pk_add_f32 v[46:47], v[52:53], v[126:127]
	v_lshlrev_b32_e32 v138, 16, v241
	v_and_b32_e32 v139, 0xffff0000, v241
	v_pk_add_f32 v[48:49], v[50:51], v[124:125]
	v_cvt_pk_bf16_f32 v51, v46, v47
	v_mul_f32_e32 v47, v47, v47
	v_pk_add_f32 v[42:43], v[42:43], v[128:129]
	v_fmac_f32_e32 v47, v46, v46
	v_pk_add_f32 v[44:45], v[44:45], v[138:139]
	v_cvt_pk_bf16_f32 v46, v42, v43
	v_mul_f32_e32 v43, v43, v43
	v_cvt_pk_bf16_f32 v50, v48, v49
	v_mul_f32_e32 v49, v49, v49
	v_fmac_f32_e32 v43, v42, v42
	v_mul_f32_e32 v42, v45, v45
	v_lshlrev_b32_e32 v140, 16, v238
	v_and_b32_e32 v141, 0xffff0000, v238
	v_fmac_f32_e32 v49, v48, v48
	v_fmac_f32_e32 v42, v44, v44
	v_lshlrev_b32_e32 v142, 16, v239
	v_and_b32_e32 v143, 0xffff0000, v239
	v_add_f32_e32 v48, v49, v47
	v_add_f32_e32 v42, v43, v42
	v_pk_add_f32 v[38:39], v[38:39], v[140:141]
	v_cvt_pk_bf16_f32 v47, v44, v45
	v_add_f32_e32 v44, v48, v42
	v_pk_add_f32 v[40:41], v[40:41], v[142:143]
	v_cvt_pk_bf16_f32 v42, v38, v39
	v_mul_f32_e32 v39, v39, v39
	v_fmac_f32_e32 v39, v38, v38
	v_mul_f32_e32 v38, v41, v41
	v_lshlrev_b32_e32 v144, 16, v236
	v_and_b32_e32 v145, 0xffff0000, v236
	v_fmac_f32_e32 v38, v40, v40
	v_lshlrev_b32_e32 v146, 16, v237
	v_and_b32_e32 v147, 0xffff0000, v237
	v_add_f32_e32 v38, v39, v38
	v_pk_add_f32 v[30:31], v[30:31], v[144:145]
	v_cvt_pk_bf16_f32 v43, v40, v41
	v_add_f32_e32 v40, v44, v38
	v_pk_add_f32 v[32:33], v[32:33], v[146:147]
	v_cvt_pk_bf16_f32 v38, v30, v31
	v_mul_f32_e32 v31, v31, v31
	v_fmac_f32_e32 v31, v30, v30
	v_mul_f32_e32 v30, v33, v33
	v_lshl_add_u64 v[52:53], s[4:5], 0, v[94:95]
	v_fmac_f32_e32 v30, v32, v32
	v_lshlrev_b32_e32 v150, 16, v199
	v_and_b32_e32 v151, 0xffff0000, v199
	v_lshl_add_u64 v[52:53], v[52:53], 0, v[136:137]
	v_cvt_pk_bf16_f32 v39, v32, v33
	v_add_f32_e32 v30, v31, v30
	v_lshlrev_b32_e32 v148, 16, v198
	v_and_b32_e32 v149, 0xffff0000, v198
	v_lshlrev_b32_e32 v152, 16, v196
	v_and_b32_e32 v153, 0xffff0000, v196
	global_store_dwordx2 v[52:53], v[38:39], off offset:288
	v_add_f32_e32 v38, v40, v30
	v_pk_add_f32 v[30:31], v[36:37], v[150:151]
	v_lshlrev_b32_e32 v154, 16, v197
	v_and_b32_e32 v155, 0xffff0000, v197
	v_pk_add_f32 v[32:33], v[34:35], v[148:149]
	v_cvt_pk_bf16_f32 v35, v30, v31
	v_mul_f32_e32 v31, v31, v31
	v_pk_add_f32 v[26:27], v[26:27], v[152:153]
	v_fmac_f32_e32 v31, v30, v30
	v_pk_add_f32 v[28:29], v[28:29], v[154:155]
	v_cvt_pk_bf16_f32 v30, v26, v27
	v_mul_f32_e32 v27, v27, v27
	v_cvt_pk_bf16_f32 v34, v32, v33
	v_mul_f32_e32 v33, v33, v33
	v_fmac_f32_e32 v27, v26, v26
	v_mul_f32_e32 v26, v29, v29
	v_lshlrev_b32_e32 v156, 16, v194
	v_and_b32_e32 v157, 0xffff0000, v194
	v_fmac_f32_e32 v33, v32, v32
	v_fmac_f32_e32 v26, v28, v28
	v_lshlrev_b32_e32 v96, 16, v195
	v_and_b32_e32 v97, 0xffff0000, v195
	v_add_f32_e32 v32, v33, v31
	v_add_f32_e32 v26, v27, v26
	v_pk_add_f32 v[22:23], v[22:23], v[156:157]
	v_cvt_pk_bf16_f32 v31, v28, v29
	v_add_f32_e32 v28, v32, v26
	v_pk_add_f32 v[24:25], v[24:25], v[96:97]
	v_cvt_pk_bf16_f32 v26, v22, v23
	v_mul_f32_e32 v23, v23, v23
	v_fmac_f32_e32 v23, v22, v22
	v_mul_f32_e32 v22, v25, v25
	v_lshlrev_b32_e32 v88, 16, v192
	v_and_b32_e32 v89, 0xffff0000, v192
	v_fmac_f32_e32 v22, v24, v24
	v_lshlrev_b32_e32 v90, 16, v193
	v_and_b32_e32 v91, 0xffff0000, v193
	v_add_f32_e32 v22, v23, v22
	v_pk_add_f32 v[14:15], v[14:15], v[88:89]
	v_cvt_pk_bf16_f32 v27, v24, v25
	v_add_f32_e32 v24, v28, v22
	v_pk_add_f32 v[16:17], v[16:17], v[90:91]
	v_cvt_pk_bf16_f32 v22, v14, v15
	v_mul_f32_e32 v15, v15, v15
	v_fmac_f32_e32 v15, v14, v14
	v_mul_f32_e32 v14, v17, v17
	v_lshl_add_u64 v[36:37], s[4:5], 0, v[80:81]
	v_fmac_f32_e32 v14, v16, v16
	v_lshlrev_b32_e32 v86, 16, v191
	v_and_b32_e32 v87, 0xffff0000, v191
	v_lshl_add_u64 v[36:37], v[36:37], 0, v[136:137]
	v_cvt_pk_bf16_f32 v23, v16, v17
	v_add_f32_e32 v14, v15, v14
	v_lshlrev_b32_e32 v84, 16, v190
	v_and_b32_e32 v85, 0xffff0000, v190
	v_lshlrev_b32_e32 v78, 16, v188
	v_and_b32_e32 v79, 0xffff0000, v188
	global_store_dwordx2 v[36:37], v[22:23], off offset:288
	v_add_f32_e32 v22, v24, v14
	v_pk_add_f32 v[14:15], v[20:21], v[86:87]
	v_lshlrev_b32_e32 v82, 16, v189
	v_and_b32_e32 v83, 0xffff0000, v189
	v_pk_add_f32 v[16:17], v[18:19], v[84:85]
	v_cvt_pk_bf16_f32 v19, v14, v15
	v_mul_f32_e32 v15, v15, v15
	v_pk_add_f32 v[10:11], v[10:11], v[78:79]
	v_fmac_f32_e32 v15, v14, v14
	v_pk_add_f32 v[12:13], v[12:13], v[82:83]
	v_cvt_pk_bf16_f32 v14, v10, v11
	v_mul_f32_e32 v11, v11, v11
	v_cvt_pk_bf16_f32 v18, v16, v17
	v_mul_f32_e32 v17, v17, v17
	v_fmac_f32_e32 v11, v10, v10
	v_mul_f32_e32 v10, v13, v13
	v_lshlrev_b32_e32 v74, 16, v186
	v_and_b32_e32 v75, 0xffff0000, v186
	v_fmac_f32_e32 v17, v16, v16
	v_fmac_f32_e32 v10, v12, v12
	v_lshlrev_b32_e32 v76, 16, v187
	v_and_b32_e32 v77, 0xffff0000, v187
	v_add_f32_e32 v16, v17, v15
	v_add_f32_e32 v10, v11, v10
	v_pk_add_f32 v[6:7], v[6:7], v[74:75]
	v_cvt_pk_bf16_f32 v15, v12, v13
	v_add_f32_e32 v12, v16, v10
	v_pk_add_f32 v[8:9], v[8:9], v[76:77]
	v_cvt_pk_bf16_f32 v10, v6, v7
	v_mul_f32_e32 v7, v7, v7
	v_fmac_f32_e32 v7, v6, v6
	v_mul_f32_e32 v6, v9, v9
	v_fmac_f32_e32 v6, v8, v8
	v_add_f32_e32 v6, v7, v6
	v_pk_add_f32 v[2:3], v[2:3], v[70:71]
	v_cvt_pk_bf16_f32 v11, v8, v9
	v_add_f32_e32 v8, v12, v6
	v_pk_add_f32 v[4:5], v[4:5], v[72:73]
	v_cvt_pk_bf16_f32 v6, v2, v3
	v_mul_f32_e32 v3, v3, v3
	v_fmac_f32_e32 v3, v2, v2
	v_mul_f32_e32 v2, v5, v5
	v_fmac_f32_e32 v2, v4, v4
	v_lshl_add_u64 v[20:21], s[4:5], 0, v[68:69]
	v_add_f32_e32 v2, v3, v2
	v_lshl_add_u64 v[20:21], v[20:21], 0, v[136:137]
	v_cvt_pk_bf16_f32 v7, v4, v5
	v_add_f32_e32 v5, v8, v2
	global_store_dwordx2 v[20:21], v[6:7], off offset:288
	v_mov_b32_e32 v2, v54
	v_mov_b32_e32 v3, v38
	v_mov_b32_e32 v4, v22
	v_mov_b32_e32 v6, v5
	v_permlane16_swap_b32_e32 v54, v2
	v_permlane16_swap_b32_e32 v38, v3
	v_permlane16_swap_b32_e32 v22, v4
	v_permlane16_swap_b32_e32 v5, v6
	v_add_f32_e32 v2, v54, v2
	v_add_f32_e32 v3, v38, v3
	v_add_f32_e32 v4, v22, v4
	v_add_f32_e32 v6, v5, v6
	v_mov_b32_e32 v5, v2
	v_mov_b32_e32 v7, v3
	v_mov_b32_e32 v8, v4
	v_mov_b32_e32 v9, v6
	v_permlane32_swap_b32_e32 v2, v5
	v_permlane32_swap_b32_e32 v3, v7
	v_permlane32_swap_b32_e32 v4, v8
	v_permlane32_swap_b32_e32 v6, v9
	global_store_dwordx2 v[92:93], v[98:99], off
	global_store_dwordx2 v[92:93], v[62:63], off offset:32
	global_store_dwordx2 v[92:93], v[58:59], off offset:256
	global_store_dwordx2 v[52:53], v[50:51], off
	global_store_dwordx2 v[52:53], v[46:47], off offset:32
	global_store_dwordx2 v[52:53], v[42:43], off offset:256
	global_store_dwordx2 v[36:37], v[34:35], off
	global_store_dwordx2 v[36:37], v[30:31], off offset:32
	global_store_dwordx2 v[36:37], v[26:27], off offset:256
	global_store_dwordx2 v[20:21], v[18:19], off
	global_store_dwordx2 v[20:21], v[14:15], off offset:32
	global_store_dwordx2 v[20:21], v[10:11], off offset:256
	s_lshl_b32 s20, s42, 2
	s_ashr_i32 s21, s20, 31
	s_lshl_b64 s[20:21], s[20:21], 2
	s_add_u32 s20, s39, s20
	s_addc_u32 s21, s40, s21
	v_add_f32_e32 v7, v3, v7
	v_add_f32_e32 v5, v2, v5
	v_add_f32_e32 v4, v4, v8
	v_add_f32_e32 v6, v6, v9
	v_lshrrev_b32_e32 v8, 4, v212
	v_add_u32_e32 v10, 0x80, v66
	v_ashrrev_i32_e32 v11, 31, v10
	v_cmp_eq_u32_e64 s[18:19], 1, v8
	v_lshlrev_b64 v[2:3], 6, v[10:11]
	v_lshl_add_u64 v[2:3], s[20:21], 0, v[2:3]
	v_cndmask_b32_e64 v5, v5, v7, s[18:19]
	v_cmp_eq_u32_e64 s[18:19], 2, v8
	s_nop 1
	v_cndmask_b32_e64 v5, v5, v4, s[18:19]
	v_cmp_eq_u32_e64 s[18:19], 3, v8
	s_nop 1
	v_cndmask_b32_e64 v5, v5, v6, s[18:19]
	global_store_dword v[2:3], v5, off
.LBB0_1015:
	s_andn2_b64 vcc, exec, s[6:7]
	s_mov_b64 s[6:7], -1
	s_cbranch_vccnz .LBB0_1000
	s_andn2_b64 vcc, exec, s[2:3]
	s_cbranch_vccnz .LBB0_999
	s_barrier
	s_branch .LBB0_999

.LBB0_1345:
	v_mov_b32_e32 v184, v212
	s_lshl_b32 s14, s40, 8
	v_ashrrev_i32_e32 v136, 2, v184
	s_or_b32 s14, s14, s36
	v_and_b32_e32 v136, -4, v136
	v_add_u32_e32 v136, s14, v136
	v_and_or_b32 v138, v184, 15, s31
	s_lshl_b32 s14, s43, 8
	v_ashrrev_i32_e32 v137, 31, v136
	v_add_u32_e32 v140, s14, v138
	v_lshlrev_b64 v[136:137], 1, v[136:137]
	v_ashrrev_i32_e32 v141, 31, v140
	v_or_b32_e32 v150, 16, v140
	v_lshl_add_u64 v[138:139], s[2:3], 0, v[136:137]
	v_lshlrev_b64 v[168:169], 11, v[140:141]
	v_ashrrev_i32_e32 v151, 31, v150
	v_or_b32_e32 v154, 32, v140
	v_lshl_add_u64 v[142:143], v[138:139], 0, v[168:169]
	v_lshlrev_b64 v[170:171], 11, v[150:151]
	v_ashrrev_i32_e32 v155, 31, v154
	global_load_dwordx2 v[144:145], v[142:143], off
	global_load_dwordx2 v[146:147], v[142:143], off offset:32
	global_load_dwordx2 v[148:149], v[142:143], off offset:256
	global_load_dwordx2 v[152:153], v[142:143], off offset:288
	v_lshl_add_u64 v[142:143], v[138:139], 0, v[170:171]
	v_lshlrev_b64 v[154:155], 11, v[154:155]
	v_or_b32_e32 v174, 48, v140
	global_load_dwordx2 v[150:151], v[142:143], off
	global_load_dwordx2 v[156:157], v[142:143], off offset:32
	global_load_dwordx2 v[158:159], v[142:143], off offset:256
	global_load_dwordx2 v[160:161], v[142:143], off offset:288
	v_lshl_add_u64 v[142:143], v[138:139], 0, v[154:155]
	v_ashrrev_i32_e32 v175, 31, v174
	global_load_dwordx2 v[162:163], v[142:143], off
	global_load_dwordx2 v[164:165], v[142:143], off offset:32
	global_load_dwordx2 v[172:173], v[142:143], off offset:256
	global_load_dwordx2 v[176:177], v[142:143], off offset:288
	v_lshlrev_b64 v[142:143], 11, v[174:175]
	v_lshl_add_u64 v[174:175], v[138:139], 0, v[142:143]
	global_load_dwordx2 v[178:179], v[174:175], off
	global_load_dwordx2 v[180:181], v[174:175], off offset:32
	global_load_dwordx2 v[182:183], v[174:175], off offset:256
	s_nop 0
	global_load_dwordx2 v[174:175], v[174:175], off offset:288
	v_cmp_gt_u32_e32 vcc, 16, v184
	v_add_u32_e32 v141, s31, v184
	v_lshl_add_u64 v[168:169], s[2:3], 0, v[168:169]
	v_lshl_add_u64 v[168:169], v[168:169], 0, v[136:137]
	s_waitcnt vmcnt(0)
	v_lshlrev_b32_e32 v184, 16, v144
	v_and_b32_e32 v185, 0xffff0000, v144
	v_lshlrev_b32_e32 v186, 16, v145
	v_and_b32_e32 v187, 0xffff0000, v145
	v_pk_add_f32 v[126:127], v[126:127], v[184:185]
	v_pk_add_f32 v[128:129], v[128:129], v[186:187]
	v_lshlrev_b32_e32 v188, 16, v146
	v_and_b32_e32 v189, 0xffff0000, v146
	v_lshlrev_b32_e32 v190, 16, v147
	v_and_b32_e32 v191, 0xffff0000, v147
	v_pk_add_f32 v[122:123], v[122:123], v[188:189]
	v_pk_add_f32 v[124:125], v[124:125], v[190:191]
	v_lshlrev_b32_e32 v192, 16, v148
	v_and_b32_e32 v193, 0xffff0000, v148
	v_lshlrev_b32_e32 v194, 16, v149
	v_lshlrev_b32_e32 v144, 16, v174
	v_and_b32_e32 v145, 0xffff0000, v174
	v_cvt_pk_bf16_f32 v174, v126, v127
	v_mul_f32_e32 v127, v127, v127
	v_fmac_f32_e32 v127, v126, v126
	v_mul_f32_e32 v126, v129, v129
	v_fmac_f32_e32 v126, v128, v128
	v_lshlrev_b32_e32 v146, 16, v175
	v_and_b32_e32 v147, 0xffff0000, v175
	v_cvt_pk_bf16_f32 v175, v128, v129
	v_add_f32_e32 v128, v127, v126
	v_cvt_pk_bf16_f32 v126, v122, v123
	v_mul_f32_e32 v123, v123, v123
	v_fmac_f32_e32 v123, v122, v122
	v_mul_f32_e32 v122, v125, v125
	v_fmac_f32_e32 v122, v124, v124
	v_and_b32_e32 v195, 0xffff0000, v149
	v_add_f32_e32 v122, v123, v122
	v_pk_add_f32 v[118:119], v[118:119], v[192:193]
	v_cvt_pk_bf16_f32 v127, v124, v125
	v_add_f32_e32 v124, v128, v122
	v_pk_add_f32 v[120:121], v[120:121], v[194:195]
	v_cvt_pk_bf16_f32 v122, v118, v119
	v_mul_f32_e32 v119, v119, v119
	v_fmac_f32_e32 v119, v118, v118
	v_mul_f32_e32 v118, v121, v121
	v_lshlrev_b32_e32 v196, 16, v152
	v_and_b32_e32 v197, 0xffff0000, v152
	v_fmac_f32_e32 v118, v120, v120
	v_lshlrev_b32_e32 v198, 16, v153
	v_and_b32_e32 v199, 0xffff0000, v153
	v_add_f32_e32 v118, v119, v118
	v_pk_add_f32 v[110:111], v[110:111], v[196:197]
	v_cvt_pk_bf16_f32 v123, v120, v121
	v_add_f32_e32 v120, v124, v118
	v_pk_add_f32 v[112:113], v[112:113], v[198:199]
	v_cvt_pk_bf16_f32 v118, v110, v111
	v_mul_f32_e32 v111, v111, v111
	v_fmac_f32_e32 v111, v110, v110
	v_mul_f32_e32 v110, v113, v113
	v_fmac_f32_e32 v110, v112, v112
	v_lshlrev_b32_e32 v202, 16, v151
	v_and_b32_e32 v203, 0xffff0000, v151
	v_cvt_pk_bf16_f32 v119, v112, v113
	v_add_f32_e32 v110, v111, v110
	v_lshlrev_b32_e32 v200, 16, v150
	v_and_b32_e32 v201, 0xffff0000, v150
	v_lshlrev_b32_e32 v204, 16, v156
	v_and_b32_e32 v205, 0xffff0000, v156
	global_store_dwordx2 v[168:169], v[118:119], off offset:288
	v_add_u32_e32 v128, 0x80, v140
	v_ashrrev_i32_e32 v129, 31, v128
	v_lshlrev_b64 v[128:129], 11, v[128:129]
	v_lshl_add_u64 v[128:129], v[138:139], 0, v[128:129]
	v_mov_b32_e32 v124, 0x8000
	v_mov_b32_e32 v125, 0
	global_load_dwordx2 v[250:251], v[128:129], off
	global_load_dwordx2 v[248:249], v[128:129], off offset:32
	global_load_dwordx2 v[246:247], v[128:129], off offset:256
	global_load_dwordx2 v[244:245], v[128:129], off offset:288
	v_lshl_add_u64 v[128:129], v[128:129], 0, v[124:125]
	global_load_dwordx2 v[242:243], v[128:129], off
	global_load_dwordx2 v[240:241], v[128:129], off offset:32
	global_load_dwordx2 v[238:239], v[128:129], off offset:256
	global_load_dwordx2 v[236:237], v[128:129], off offset:288
	v_lshl_add_u64 v[128:129], v[128:129], 0, v[124:125]
	global_load_dwordx2 v[198:199], v[128:129], off
	global_load_dwordx2 v[196:197], v[128:129], off offset:32
	global_load_dwordx2 v[194:195], v[128:129], off offset:256
	global_load_dwordx2 v[192:193], v[128:129], off offset:288
	v_lshl_add_u64 v[128:129], v[128:129], 0, v[124:125]
	global_load_dwordx2 v[190:191], v[128:129], off
	global_load_dwordx2 v[188:189], v[128:129], off offset:32
	global_load_dwordx2 v[186:187], v[128:129], off offset:256
	global_load_dwordx2 v[184:185], v[128:129], off offset:288
	v_add_f32_e32 v118, v120, v110
	v_pk_add_f32 v[110:111], v[116:117], v[202:203]
	v_lshlrev_b32_e32 v206, 16, v157
	v_and_b32_e32 v207, 0xffff0000, v157
	v_pk_add_f32 v[112:113], v[114:115], v[200:201]
	v_cvt_pk_bf16_f32 v115, v110, v111
	v_mul_f32_e32 v111, v111, v111
	v_pk_add_f32 v[106:107], v[106:107], v[204:205]
	v_fmac_f32_e32 v111, v110, v110
	v_pk_add_f32 v[108:109], v[108:109], v[206:207]
	v_cvt_pk_bf16_f32 v110, v106, v107
	v_mul_f32_e32 v107, v107, v107
	v_cvt_pk_bf16_f32 v114, v112, v113
	v_mul_f32_e32 v113, v113, v113
	v_fmac_f32_e32 v107, v106, v106
	v_mul_f32_e32 v106, v109, v109
	v_lshlrev_b32_e32 v210, 16, v158
	v_and_b32_e32 v211, 0xffff0000, v158
	v_fmac_f32_e32 v113, v112, v112
	v_fmac_f32_e32 v106, v108, v108
	v_lshlrev_b32_e32 v214, 16, v159
	v_and_b32_e32 v215, 0xffff0000, v159
	v_add_f32_e32 v112, v113, v111
	v_add_f32_e32 v106, v107, v106
	v_pk_add_f32 v[102:103], v[102:103], v[210:211]
	v_cvt_pk_bf16_f32 v111, v108, v109
	v_add_f32_e32 v108, v112, v106
	v_pk_add_f32 v[104:105], v[104:105], v[214:215]
	v_cvt_pk_bf16_f32 v106, v102, v103
	v_mul_f32_e32 v103, v103, v103
	v_fmac_f32_e32 v103, v102, v102
	v_mul_f32_e32 v102, v105, v105
	v_lshlrev_b32_e32 v216, 16, v160
	v_and_b32_e32 v217, 0xffff0000, v160
	v_fmac_f32_e32 v102, v104, v104
	v_lshlrev_b32_e32 v224, 16, v161
	v_and_b32_e32 v225, 0xffff0000, v161
	v_add_f32_e32 v102, v103, v102
	v_pk_add_f32 v[94:95], v[94:95], v[216:217]
	v_cvt_pk_bf16_f32 v107, v104, v105
	v_add_f32_e32 v104, v108, v102
	v_pk_add_f32 v[96:97], v[96:97], v[224:225]
	v_cvt_pk_bf16_f32 v102, v94, v95
	v_mul_f32_e32 v95, v95, v95
	v_fmac_f32_e32 v95, v94, v94
	v_mul_f32_e32 v94, v97, v97
	v_lshl_add_u64 v[116:117], s[2:3], 0, v[170:171]
	v_fmac_f32_e32 v94, v96, v96
	v_lshlrev_b32_e32 v228, 16, v163
	v_and_b32_e32 v229, 0xffff0000, v163
	v_lshl_add_u64 v[116:117], v[116:117], 0, v[136:137]
	v_cvt_pk_bf16_f32 v103, v96, v97
	v_add_f32_e32 v94, v95, v94
	v_lshlrev_b32_e32 v226, 16, v162
	v_and_b32_e32 v227, 0xffff0000, v162
	v_lshlrev_b32_e32 v230, 16, v164
	v_and_b32_e32 v231, 0xffff0000, v164
	global_store_dwordx2 v[116:117], v[102:103], off offset:288
	v_add_f32_e32 v102, v104, v94
	v_pk_add_f32 v[94:95], v[100:101], v[228:229]
	v_lshlrev_b32_e32 v232, 16, v165
	v_and_b32_e32 v233, 0xffff0000, v165
	v_pk_add_f32 v[96:97], v[98:99], v[226:227]
	v_cvt_pk_bf16_f32 v99, v94, v95
	v_mul_f32_e32 v95, v95, v95
	v_pk_add_f32 v[90:91], v[90:91], v[230:231]
	v_fmac_f32_e32 v95, v94, v94
	v_pk_add_f32 v[92:93], v[92:93], v[232:233]
	v_cvt_pk_bf16_f32 v94, v90, v91
	v_mul_f32_e32 v91, v91, v91
	v_cvt_pk_bf16_f32 v98, v96, v97
	v_mul_f32_e32 v97, v97, v97
	v_fmac_f32_e32 v91, v90, v90
	v_mul_f32_e32 v90, v93, v93
	v_lshlrev_b32_e32 v234, 16, v172
	v_and_b32_e32 v235, 0xffff0000, v172
	v_fmac_f32_e32 v97, v96, v96
	v_fmac_f32_e32 v90, v92, v92
	v_lshlrev_b32_e32 v172, 16, v173
	v_and_b32_e32 v173, 0xffff0000, v173
	v_add_f32_e32 v96, v97, v95
	v_add_f32_e32 v90, v91, v90
	v_pk_add_f32 v[86:87], v[86:87], v[234:235]
	v_cvt_pk_bf16_f32 v95, v92, v93
	v_add_f32_e32 v92, v96, v90
	v_pk_add_f32 v[88:89], v[88:89], v[172:173]
	v_cvt_pk_bf16_f32 v90, v86, v87
	v_mul_f32_e32 v87, v87, v87
	v_fmac_f32_e32 v87, v86, v86
	v_mul_f32_e32 v86, v89, v89
	v_lshlrev_b32_e32 v162, 16, v176
	v_and_b32_e32 v163, 0xffff0000, v176
	v_fmac_f32_e32 v86, v88, v88
	v_lshlrev_b32_e32 v164, 16, v177
	v_and_b32_e32 v165, 0xffff0000, v177
	v_add_f32_e32 v86, v87, v86
	v_pk_add_f32 v[78:79], v[78:79], v[162:163]
	v_cvt_pk_bf16_f32 v91, v88, v89
	v_add_f32_e32 v88, v92, v86
	v_pk_add_f32 v[80:81], v[80:81], v[164:165]
	v_cvt_pk_bf16_f32 v86, v78, v79
	v_mul_f32_e32 v79, v79, v79
	v_fmac_f32_e32 v79, v78, v78
	v_mul_f32_e32 v78, v81, v81
	v_lshl_add_u64 v[100:101], s[2:3], 0, v[154:155]
	v_fmac_f32_e32 v78, v80, v80
	v_lshlrev_b32_e32 v160, 16, v179
	v_and_b32_e32 v161, 0xffff0000, v179
	v_lshl_add_u64 v[100:101], v[100:101], 0, v[136:137]
	v_cvt_pk_bf16_f32 v87, v80, v81
	v_add_f32_e32 v78, v79, v78
	v_lshlrev_b32_e32 v158, 16, v178
	v_and_b32_e32 v159, 0xffff0000, v178
	v_lshlrev_b32_e32 v152, 16, v180
	v_and_b32_e32 v153, 0xffff0000, v180
	global_store_dwordx2 v[100:101], v[86:87], off offset:288
	v_add_f32_e32 v86, v88, v78
	v_pk_add_f32 v[78:79], v[84:85], v[160:161]
	v_lshlrev_b32_e32 v156, 16, v181
	v_and_b32_e32 v157, 0xffff0000, v181
	v_pk_add_f32 v[80:81], v[82:83], v[158:159]
	v_cvt_pk_bf16_f32 v83, v78, v79
	v_mul_f32_e32 v79, v79, v79
	v_pk_add_f32 v[74:75], v[74:75], v[152:153]
	v_fmac_f32_e32 v79, v78, v78
	v_pk_add_f32 v[76:77], v[76:77], v[156:157]
	v_cvt_pk_bf16_f32 v78, v74, v75
	v_mul_f32_e32 v75, v75, v75
	v_cvt_pk_bf16_f32 v82, v80, v81
	v_mul_f32_e32 v81, v81, v81
	v_fmac_f32_e32 v75, v74, v74
	v_mul_f32_e32 v74, v77, v77
	v_lshlrev_b32_e32 v148, 16, v182
	v_and_b32_e32 v149, 0xffff0000, v182
	v_fmac_f32_e32 v81, v80, v80
	v_fmac_f32_e32 v74, v76, v76
	v_lshlrev_b32_e32 v150, 16, v183
	v_and_b32_e32 v151, 0xffff0000, v183
	v_add_f32_e32 v80, v81, v79
	v_add_f32_e32 v74, v75, v74
	v_pk_add_f32 v[70:71], v[70:71], v[148:149]
	v_cvt_pk_bf16_f32 v79, v76, v77
	v_add_f32_e32 v76, v80, v74
	v_pk_add_f32 v[72:73], v[72:73], v[150:151]
	v_cvt_pk_bf16_f32 v74, v70, v71
	v_mul_f32_e32 v71, v71, v71
	v_fmac_f32_e32 v71, v70, v70
	v_mul_f32_e32 v70, v73, v73
	v_fmac_f32_e32 v70, v72, v72
	v_add_f32_e32 v70, v71, v70
	v_pk_add_f32 v[66:67], v[66:67], v[144:145]
	v_cvt_pk_bf16_f32 v75, v72, v73
	v_add_f32_e32 v72, v76, v70
	v_pk_add_f32 v[68:69], v[68:69], v[146:147]
	v_cvt_pk_bf16_f32 v70, v66, v67
	v_mul_f32_e32 v67, v67, v67
	v_fmac_f32_e32 v67, v66, v66
	v_mul_f32_e32 v66, v69, v69
	v_fmac_f32_e32 v66, v68, v68
	v_lshl_add_u64 v[84:85], s[2:3], 0, v[142:143]
	v_add_f32_e32 v66, v67, v66
	v_lshl_add_u64 v[84:85], v[84:85], 0, v[136:137]
	v_cvt_pk_bf16_f32 v71, v68, v69
	v_add_f32_e32 v66, v72, v66
	global_store_dwordx2 v[84:85], v[70:71], off offset:288
	v_mov_b32_e32 v67, v118
	v_mov_b32_e32 v68, v102
	v_mov_b32_e32 v69, v86
	v_mov_b32_e32 v70, v66
	v_permlane16_swap_b32_e32 v118, v67
	v_permlane16_swap_b32_e32 v102, v68
	v_permlane16_swap_b32_e32 v86, v69
	v_permlane16_swap_b32_e32 v66, v70
	v_add_f32_e32 v67, v118, v67
	v_add_f32_e32 v68, v102, v68
	v_add_f32_e32 v69, v86, v69
	v_add_f32_e32 v71, v66, v70
	global_store_dwordx2 v[84:85], v[74:75], off offset:256
	v_mov_b32_e32 v70, v67
	v_mov_b32_e32 v72, v68
	v_mov_b32_e32 v73, v69
	v_mov_b32_e32 v74, v71
	v_permlane32_swap_b32_e32 v67, v70
	v_permlane32_swap_b32_e32 v68, v72
	v_permlane32_swap_b32_e32 v69, v73
	v_permlane32_swap_b32_e32 v71, v74
	v_add_u32_e32 v66, s14, v141
	global_store_dwordx2 v[168:169], v[174:175], off
	global_store_dwordx2 v[168:169], v[126:127], off offset:32
	global_store_dwordx2 v[168:169], v[122:123], off offset:256
	global_store_dwordx2 v[116:117], v[114:115], off
	global_store_dwordx2 v[116:117], v[110:111], off offset:32
	global_store_dwordx2 v[116:117], v[106:107], off offset:256
	global_store_dwordx2 v[100:101], v[98:99], off
	global_store_dwordx2 v[100:101], v[94:95], off offset:32
	global_store_dwordx2 v[100:101], v[90:91], off offset:256
	global_store_dwordx2 v[84:85], v[82:83], off
	global_store_dwordx2 v[84:85], v[78:79], off offset:32
	s_lshl_b32 s16, s40, 2
	s_ashr_i32 s17, s16, 31
	s_lshl_b64 s[16:17], s[16:17], 2
	s_add_u32 s16, s34, s16
	s_addc_u32 s17, s35, s17
	v_add_f32_e32 v70, v67, v70
	v_add_f32_e32 v73, v69, v73
	v_add_f32_e32 v72, v68, v72
	v_add_f32_e32 v71, v71, v74
	v_lshrrev_b32_e32 v74, 4, v212
	v_ashrrev_i32_e32 v67, 31, v66
	v_cmp_eq_u32_e64 s[14:15], 1, v74
	v_lshlrev_b64 v[68:69], 6, v[66:67]
	v_lshl_add_u64 v[68:69], s[16:17], 0, v[68:69]
	v_cndmask_b32_e64 v70, v70, v72, s[14:15]
	v_cmp_eq_u32_e64 s[14:15], 2, v74
	s_nop 1
	v_cndmask_b32_e64 v70, v70, v73, s[14:15]
	v_cmp_eq_u32_e64 s[14:15], 3, v74
	s_nop 1
	v_cndmask_b32_e64 v70, v70, v71, s[14:15]
	global_store_dword v[68:69], v70, off
.LBB0_1347:
	v_add_u32_e32 v68, 0x80, v140
	v_ashrrev_i32_e32 v69, 31, v68
	v_add_u32_e32 v76, 0x90, v140
	v_lshlrev_b64 v[92:93], 11, v[68:69]
	v_ashrrev_i32_e32 v77, 31, v76
	v_add_u32_e32 v80, 0xa0, v140
	v_lshl_add_u64 v[68:69], v[138:139], 0, v[92:93]
	v_lshlrev_b64 v[94:95], 11, v[76:77]
	v_ashrrev_i32_e32 v81, 31, v80
	v_lshl_add_u64 v[68:69], v[138:139], 0, v[94:95]
	v_lshlrev_b64 v[80:81], 11, v[80:81]
	v_add_u32_e32 v98, 0xb0, v140
	v_lshl_add_u64 v[68:69], v[138:139], 0, v[80:81]
	v_ashrrev_i32_e32 v99, 31, v98
	v_lshlrev_b64 v[68:69], 11, v[98:99]
	v_lshl_add_u64 v[98:99], v[138:139], 0, v[68:69]
	v_lshl_add_u64 v[92:93], s[2:3], 0, v[92:93]
	v_lshl_add_u64 v[92:93], v[92:93], 0, v[136:137]
	s_waitcnt vmcnt(15)
	v_lshlrev_b32_e32 v108, 16, v250
	v_and_b32_e32 v109, 0xffff0000, v250
	v_lshlrev_b32_e32 v110, 16, v251
	v_and_b32_e32 v111, 0xffff0000, v251
	v_pk_add_f32 v[62:63], v[62:63], v[108:109]
	v_pk_add_f32 v[64:65], v[64:65], v[110:111]
	v_lshlrev_b32_e32 v112, 16, v248
	v_and_b32_e32 v113, 0xffff0000, v248
	v_lshlrev_b32_e32 v114, 16, v249
	v_and_b32_e32 v115, 0xffff0000, v249
	v_pk_add_f32 v[58:59], v[58:59], v[112:113]
	v_pk_add_f32 v[60:61], v[60:61], v[114:115]
	v_lshlrev_b32_e32 v116, 16, v246
	v_and_b32_e32 v117, 0xffff0000, v246
	v_lshlrev_b32_e32 v118, 16, v247
	v_lshlrev_b32_e32 v70, 16, v184
	v_and_b32_e32 v71, 0xffff0000, v184
	v_cvt_pk_bf16_f32 v98, v62, v63
	v_mul_f32_e32 v63, v63, v63
	v_fmac_f32_e32 v63, v62, v62
	v_mul_f32_e32 v62, v65, v65
	v_fmac_f32_e32 v62, v64, v64
	v_lshlrev_b32_e32 v72, 16, v185
	v_and_b32_e32 v73, 0xffff0000, v185
	v_cvt_pk_bf16_f32 v99, v64, v65
	v_add_f32_e32 v64, v63, v62
	v_cvt_pk_bf16_f32 v62, v58, v59
	v_mul_f32_e32 v59, v59, v59
	v_fmac_f32_e32 v59, v58, v58
	v_mul_f32_e32 v58, v61, v61
	v_fmac_f32_e32 v58, v60, v60
	v_and_b32_e32 v119, 0xffff0000, v247
	v_add_f32_e32 v58, v59, v58
	v_pk_add_f32 v[54:55], v[54:55], v[116:117]
	v_cvt_pk_bf16_f32 v63, v60, v61
	v_add_f32_e32 v60, v64, v58
	v_pk_add_f32 v[56:57], v[56:57], v[118:119]
	v_cvt_pk_bf16_f32 v58, v54, v55
	v_mul_f32_e32 v55, v55, v55
	v_fmac_f32_e32 v55, v54, v54
	v_mul_f32_e32 v54, v57, v57
	v_lshlrev_b32_e32 v120, 16, v244
	v_and_b32_e32 v121, 0xffff0000, v244
	v_fmac_f32_e32 v54, v56, v56
	v_lshlrev_b32_e32 v122, 16, v245
	v_and_b32_e32 v123, 0xffff0000, v245
	v_add_f32_e32 v54, v55, v54
	v_pk_add_f32 v[46:47], v[46:47], v[120:121]
	v_cvt_pk_bf16_f32 v59, v56, v57
	v_add_f32_e32 v56, v60, v54
	v_pk_add_f32 v[48:49], v[48:49], v[122:123]
	v_cvt_pk_bf16_f32 v54, v46, v47
	v_mul_f32_e32 v47, v47, v47
	v_fmac_f32_e32 v47, v46, v46
	v_mul_f32_e32 v46, v49, v49
	v_fmac_f32_e32 v46, v48, v48
	v_lshlrev_b32_e32 v126, 16, v243
	v_and_b32_e32 v127, 0xffff0000, v243
	v_cvt_pk_bf16_f32 v55, v48, v49
	v_add_f32_e32 v46, v47, v46
	v_lshlrev_b32_e32 v124, 16, v242
	v_and_b32_e32 v125, 0xffff0000, v242
	v_lshlrev_b32_e32 v128, 16, v240
	v_and_b32_e32 v129, 0xffff0000, v240
	global_store_dwordx2 v[92:93], v[54:55], off offset:288
	v_add_f32_e32 v54, v56, v46
	v_pk_add_f32 v[46:47], v[52:53], v[126:127]
	v_lshlrev_b32_e32 v138, 16, v241
	v_and_b32_e32 v139, 0xffff0000, v241
	v_pk_add_f32 v[48:49], v[50:51], v[124:125]
	v_cvt_pk_bf16_f32 v51, v46, v47
	v_mul_f32_e32 v47, v47, v47
	v_pk_add_f32 v[42:43], v[42:43], v[128:129]
	v_fmac_f32_e32 v47, v46, v46
	v_pk_add_f32 v[44:45], v[44:45], v[138:139]
	v_cvt_pk_bf16_f32 v46, v42, v43
	v_mul_f32_e32 v43, v43, v43
	v_cvt_pk_bf16_f32 v50, v48, v49
	v_mul_f32_e32 v49, v49, v49
	v_fmac_f32_e32 v43, v42, v42
	v_mul_f32_e32 v42, v45, v45
	v_lshlrev_b32_e32 v140, 16, v238
	v_and_b32_e32 v141, 0xffff0000, v238
	v_fmac_f32_e32 v49, v48, v48
	v_fmac_f32_e32 v42, v44, v44
	v_lshlrev_b32_e32 v142, 16, v239
	v_and_b32_e32 v143, 0xffff0000, v239
	v_add_f32_e32 v48, v49, v47
	v_add_f32_e32 v42, v43, v42
	v_pk_add_f32 v[38:39], v[38:39], v[140:141]
	v_cvt_pk_bf16_f32 v47, v44, v45
	v_add_f32_e32 v44, v48, v42
	v_pk_add_f32 v[40:41], v[40:41], v[142:143]
	v_cvt_pk_bf16_f32 v42, v38, v39
	v_mul_f32_e32 v39, v39, v39
	v_fmac_f32_e32 v39, v38, v38
	v_mul_f32_e32 v38, v41, v41
	v_lshlrev_b32_e32 v144, 16, v236
	v_and_b32_e32 v145, 0xffff0000, v236
	v_fmac_f32_e32 v38, v40, v40
	v_lshlrev_b32_e32 v146, 16, v237
	v_and_b32_e32 v147, 0xffff0000, v237
	v_add_f32_e32 v38, v39, v38
	v_pk_add_f32 v[30:31], v[30:31], v[144:145]
	v_cvt_pk_bf16_f32 v43, v40, v41
	v_add_f32_e32 v40, v44, v38
	v_pk_add_f32 v[32:33], v[32:33], v[146:147]
	v_cvt_pk_bf16_f32 v38, v30, v31
	v_mul_f32_e32 v31, v31, v31
	v_fmac_f32_e32 v31, v30, v30
	v_mul_f32_e32 v30, v33, v33
	v_lshl_add_u64 v[52:53], s[2:3], 0, v[94:95]
	v_fmac_f32_e32 v30, v32, v32
	v_lshlrev_b32_e32 v150, 16, v199
	v_and_b32_e32 v151, 0xffff0000, v199
	v_lshl_add_u64 v[52:53], v[52:53], 0, v[136:137]
	v_cvt_pk_bf16_f32 v39, v32, v33
	v_add_f32_e32 v30, v31, v30
	v_lshlrev_b32_e32 v148, 16, v198
	v_and_b32_e32 v149, 0xffff0000, v198
	v_lshlrev_b32_e32 v152, 16, v196
	v_and_b32_e32 v153, 0xffff0000, v196
	global_store_dwordx2 v[52:53], v[38:39], off offset:288
	v_add_f32_e32 v38, v40, v30
	v_pk_add_f32 v[30:31], v[36:37], v[150:151]
	v_lshlrev_b32_e32 v154, 16, v197
	v_and_b32_e32 v155, 0xffff0000, v197
	v_pk_add_f32 v[32:33], v[34:35], v[148:149]
	v_cvt_pk_bf16_f32 v35, v30, v31
	v_mul_f32_e32 v31, v31, v31
	v_pk_add_f32 v[26:27], v[26:27], v[152:153]
	v_fmac_f32_e32 v31, v30, v30
	v_pk_add_f32 v[28:29], v[28:29], v[154:155]
	v_cvt_pk_bf16_f32 v30, v26, v27
	v_mul_f32_e32 v27, v27, v27
	v_cvt_pk_bf16_f32 v34, v32, v33
	v_mul_f32_e32 v33, v33, v33
	v_fmac_f32_e32 v27, v26, v26
	v_mul_f32_e32 v26, v29, v29
	v_lshlrev_b32_e32 v156, 16, v194
	v_and_b32_e32 v157, 0xffff0000, v194
	v_fmac_f32_e32 v33, v32, v32
	v_fmac_f32_e32 v26, v28, v28
	v_lshlrev_b32_e32 v96, 16, v195
	v_and_b32_e32 v97, 0xffff0000, v195
	v_add_f32_e32 v32, v33, v31
	v_add_f32_e32 v26, v27, v26
	v_pk_add_f32 v[22:23], v[22:23], v[156:157]
	v_cvt_pk_bf16_f32 v31, v28, v29
	v_add_f32_e32 v28, v32, v26
	v_pk_add_f32 v[24:25], v[24:25], v[96:97]
	v_cvt_pk_bf16_f32 v26, v22, v23
	v_mul_f32_e32 v23, v23, v23
	v_fmac_f32_e32 v23, v22, v22
	v_mul_f32_e32 v22, v25, v25
	v_lshlrev_b32_e32 v88, 16, v192
	v_and_b32_e32 v89, 0xffff0000, v192
	v_fmac_f32_e32 v22, v24, v24
	v_lshlrev_b32_e32 v90, 16, v193
	v_and_b32_e32 v91, 0xffff0000, v193
	v_add_f32_e32 v22, v23, v22
	v_pk_add_f32 v[14:15], v[14:15], v[88:89]
	v_cvt_pk_bf16_f32 v27, v24, v25
	v_add_f32_e32 v24, v28, v22
	v_pk_add_f32 v[16:17], v[16:17], v[90:91]
	v_cvt_pk_bf16_f32 v22, v14, v15
	v_mul_f32_e32 v15, v15, v15
	v_fmac_f32_e32 v15, v14, v14
	v_mul_f32_e32 v14, v17, v17
	v_lshl_add_u64 v[36:37], s[2:3], 0, v[80:81]
	v_fmac_f32_e32 v14, v16, v16
	v_lshlrev_b32_e32 v86, 16, v191
	v_and_b32_e32 v87, 0xffff0000, v191
	v_lshl_add_u64 v[36:37], v[36:37], 0, v[136:137]
	v_cvt_pk_bf16_f32 v23, v16, v17
	v_add_f32_e32 v14, v15, v14
	v_lshlrev_b32_e32 v84, 16, v190
	v_and_b32_e32 v85, 0xffff0000, v190
	v_lshlrev_b32_e32 v78, 16, v188
	v_and_b32_e32 v79, 0xffff0000, v188
	global_store_dwordx2 v[36:37], v[22:23], off offset:288
	v_add_f32_e32 v22, v24, v14
	v_pk_add_f32 v[14:15], v[20:21], v[86:87]
	v_lshlrev_b32_e32 v82, 16, v189
	v_and_b32_e32 v83, 0xffff0000, v189
	v_pk_add_f32 v[16:17], v[18:19], v[84:85]
	v_cvt_pk_bf16_f32 v19, v14, v15
	v_mul_f32_e32 v15, v15, v15
	v_pk_add_f32 v[10:11], v[10:11], v[78:79]
	v_fmac_f32_e32 v15, v14, v14
	v_pk_add_f32 v[12:13], v[12:13], v[82:83]
	v_cvt_pk_bf16_f32 v14, v10, v11
	v_mul_f32_e32 v11, v11, v11
	v_cvt_pk_bf16_f32 v18, v16, v17
	v_mul_f32_e32 v17, v17, v17
	v_fmac_f32_e32 v11, v10, v10
	v_mul_f32_e32 v10, v13, v13
	v_lshlrev_b32_e32 v74, 16, v186
	v_and_b32_e32 v75, 0xffff0000, v186
	v_fmac_f32_e32 v17, v16, v16
	v_fmac_f32_e32 v10, v12, v12
	v_lshlrev_b32_e32 v76, 16, v187
	v_and_b32_e32 v77, 0xffff0000, v187
	v_add_f32_e32 v16, v17, v15
	v_add_f32_e32 v10, v11, v10
	v_pk_add_f32 v[6:7], v[6:7], v[74:75]
	v_cvt_pk_bf16_f32 v15, v12, v13
	v_add_f32_e32 v12, v16, v10
	v_pk_add_f32 v[8:9], v[8:9], v[76:77]
	v_cvt_pk_bf16_f32 v10, v6, v7
	v_mul_f32_e32 v7, v7, v7
	v_fmac_f32_e32 v7, v6, v6
	v_mul_f32_e32 v6, v9, v9
	v_fmac_f32_e32 v6, v8, v8
	v_add_f32_e32 v6, v7, v6
	v_pk_add_f32 v[2:3], v[2:3], v[70:71]
	v_cvt_pk_bf16_f32 v11, v8, v9
	v_add_f32_e32 v8, v12, v6
	v_pk_add_f32 v[4:5], v[4:5], v[72:73]
	v_cvt_pk_bf16_f32 v6, v2, v3
	v_mul_f32_e32 v3, v3, v3
	v_fmac_f32_e32 v3, v2, v2
	v_mul_f32_e32 v2, v5, v5
	v_fmac_f32_e32 v2, v4, v4
	v_lshl_add_u64 v[20:21], s[2:3], 0, v[68:69]
	v_add_f32_e32 v2, v3, v2
	v_lshl_add_u64 v[20:21], v[20:21], 0, v[136:137]
	v_cvt_pk_bf16_f32 v7, v4, v5
	v_add_f32_e32 v5, v8, v2
	global_store_dwordx2 v[20:21], v[6:7], off offset:288
	v_mov_b32_e32 v2, v54
	v_mov_b32_e32 v3, v38
	v_mov_b32_e32 v4, v22
	v_mov_b32_e32 v6, v5
	v_permlane16_swap_b32_e32 v54, v2
	v_permlane16_swap_b32_e32 v38, v3
	v_permlane16_swap_b32_e32 v22, v4
	v_permlane16_swap_b32_e32 v5, v6
	v_add_f32_e32 v2, v54, v2
	v_add_f32_e32 v3, v38, v3
	v_add_f32_e32 v4, v22, v4
	v_add_f32_e32 v6, v5, v6
	v_mov_b32_e32 v5, v2
	v_mov_b32_e32 v7, v3
	v_mov_b32_e32 v8, v4
	v_mov_b32_e32 v9, v6
	v_permlane32_swap_b32_e32 v2, v5
	v_permlane32_swap_b32_e32 v3, v7
	v_permlane32_swap_b32_e32 v4, v8
	v_permlane32_swap_b32_e32 v6, v9
	global_store_dwordx2 v[92:93], v[98:99], off
	global_store_dwordx2 v[92:93], v[62:63], off offset:32
	global_store_dwordx2 v[92:93], v[58:59], off offset:256
	global_store_dwordx2 v[52:53], v[50:51], off
	global_store_dwordx2 v[52:53], v[46:47], off offset:32
	global_store_dwordx2 v[52:53], v[42:43], off offset:256
	global_store_dwordx2 v[36:37], v[34:35], off
	global_store_dwordx2 v[36:37], v[30:31], off offset:32
	global_store_dwordx2 v[36:37], v[26:27], off offset:256
	global_store_dwordx2 v[20:21], v[18:19], off
	global_store_dwordx2 v[20:21], v[14:15], off offset:32
	global_store_dwordx2 v[20:21], v[10:11], off offset:256
	s_lshl_b32 s16, s40, 2
	s_ashr_i32 s17, s16, 31
	s_lshl_b64 s[16:17], s[16:17], 2
	s_add_u32 s16, s34, s16
	s_addc_u32 s17, s35, s17
	v_add_f32_e32 v7, v3, v7
	v_add_f32_e32 v5, v2, v5
	v_add_f32_e32 v4, v4, v8
	v_add_f32_e32 v6, v6, v9
	v_lshrrev_b32_e32 v8, 4, v212
	v_add_u32_e32 v10, 0x80, v66
	v_ashrrev_i32_e32 v11, 31, v10
	v_cmp_eq_u32_e64 s[14:15], 1, v8
	v_lshlrev_b64 v[2:3], 6, v[10:11]
	v_lshl_add_u64 v[2:3], s[16:17], 0, v[2:3]
	v_cndmask_b32_e64 v5, v5, v7, s[14:15]
	v_cmp_eq_u32_e64 s[14:15], 2, v8
	s_nop 1
	v_cndmask_b32_e64 v5, v5, v4, s[14:15]
	v_cmp_eq_u32_e64 s[14:15], 3, v8
	s_nop 1
	v_cndmask_b32_e64 v5, v5, v6, s[14:15]
	global_store_dword v[2:3], v5, off
.LBB0_1349:
	s_and_b64 vcc, exec, s[6:7]
	s_mov_b64 s[6:7], -1
	s_cbranch_vccnz .LBB0_1330
	s_andn2_b64 vcc, exec, s[4:5]
	s_cbranch_vccnz .LBB0_1329
	s_barrier
	s_branch .LBB0_1329
